# v51 + norm1 phase: per-batch adaLN parameters kept in registers, reloaded only when a wave's row crosses into another batch
# speedup vs baseline: 1.0217x; 1.0008x over previous
; __global__ void __launch_bounds__(NWAVES * 64, 2) fwd_kernel(Args args_unused) {
;     ...
;         { const int nrow = grouped ? (4 * SEQ + 4 * CTXL) : MT;
;           for (int r = gw; r < nrow; r += NGW) { const int mrow = (!grouped || r < 4 * SEQ) ? r : ML + (r - 4 * SEQ); P1_ROW(mrow); } }
.LBB0_170:
	s_cmp_lt_i32 s89, 2
	s_cselect_b64 s[10:11], -1, 0
	s_and_b64 s[0:1], s[10:11], s[20:21]
	s_andn2_b64 vcc, exec, s[0:1]
	s_cbranch_vccnz .LBB0_183
	v_mbcnt_lo_u32_b32 v128, -1, 0
	v_mbcnt_hi_u32_b32 v128, -1, v128
	s_load_dwordx2 s[12:13], s[96:97], 0xb0
	s_waitcnt lgkmcnt(0)
	s_load_dwordx2 s[4:5], s[96:97], 0
	s_waitcnt lgkmcnt(0)
	s_load_dwordx2 s[6:7], s[96:97], 16
	s_waitcnt lgkmcnt(0)
	s_movk_i32 s3, 0x4400
	s_and_b64 s[0:1], s[18:19], exec
	s_load_dwordx2 s[14:15], s[96:97], 48
	s_waitcnt lgkmcnt(0)
	s_mov_b32 s0, 0x8800
	s_cmp_ge_i32 s22, s0
	s_cbranch_scc1 .LBB0_178
	v_mbcnt_lo_u32_b32 v0, -1, 0
	v_mbcnt_hi_u32_b32 v0, -1, v0
	v_and_b32_e32 v1, 64, v0
	v_add_u32_e32 v1, 64, v1
	v_xor_b32_e32 v2, 1, v0
	v_cmp_lt_i32_e32 vcc, v2, v1
	v_lshlrev_b32_e32 v4, 2, v128
	v_ashrrev_i32_e32 v5, 31, v4
	v_cndmask_b32_e32 v2, v0, v2, vcc
	v_lshlrev_b32_e32 v6, 2, v2
	v_xor_b32_e32 v2, 2, v0
	v_cmp_lt_i32_e32 vcc, v2, v1
	s_mov_b64 s[16:17], 0x2000000
	s_mov_b32 s9, 0
	v_cndmask_b32_e32 v2, v0, v2, vcc
	v_lshlrev_b32_e32 v7, 2, v2
	v_xor_b32_e32 v2, 4, v0
	v_cmp_lt_i32_e32 vcc, v2, v1
	v_mov_b32_e32 v12, 0x358637bd
	s_mov_b32 s1, 0x800000
	v_cndmask_b32_e32 v2, v0, v2, vcc
	v_lshlrev_b32_e32 v8, 2, v2
	v_xor_b32_e32 v2, 8, v0
	v_cmp_lt_i32_e32 vcc, v2, v1
	s_movk_i32 s3, 0x1000
	s_add_i32 s37, s22, 1
	s_mul_i32 s37, s37, 17
	s_mov_b32 s56, -1
	s_mul_i32 s23, s22, 17
	s_cmp_eq_u32 s24, 0x800
	s_cselect_b32 s32, 1, s24
	s_cselect_b32 s23, s23, s22
	s_cselect_b32 s0, s37, s0
	v_cndmask_b32_e32 v2, v0, v2, vcc
	v_lshlrev_b32_e32 v9, 2, v2
	v_xor_b32_e32 v2, 16, v0
	v_cmp_lt_i32_e32 vcc, v2, v1
	s_nop 1
	v_cndmask_b32_e32 v2, v0, v2, vcc
	v_lshlrev_b32_e32 v10, 2, v2
	v_xor_b32_e32 v2, 32, v0
	v_cmp_lt_i32_e32 vcc, v2, v1
	s_nop 1
	v_cndmask_b32_e32 v0, v0, v2, vcc
	v_lshlrev_b32_e32 v11, 2, v0
	v_lshl_add_u64 v[0:1], v[4:5], 1, s[12:13]
	v_lshl_add_u64 v[0:1], v[0:1], 0, s[16:17]
	v_lshl_add_u64 v[2:3], v[4:5], 2, s[14:15]
	v_lshlrev_b64 v[4:5], 2, v[4:5]
	s_mov_b64 s[14:15], 0x1000
	s_mov_b32 s36, s23
	s_mov_b32 s34, s36
	s_cmpk_gt_i32 s34, 0x7fff
	s_cselect_b32 s20, s6, s4
	s_cselect_b32 s21, s7, s5
	s_cselect_b32 s8, 0x8000, 0
	s_sub_i32 s8, s34, s8
	s_lshl_b64 s[38:39], s[8:9], 12
	s_add_u32 s20, s20, s38
	s_addc_u32 s21, s21, s39
	v_lshl_add_u64 v[120:121], s[20:21], 0, v[4:5]
	global_load_dwordx4 v[104:107], v[120:121], off nt
	global_load_dwordx4 v[108:111], v[120:121], off offset:1024 nt
	global_load_dwordx4 v[112:115], v[120:121], off offset:3072 nt
	global_load_dwordx4 v[116:119], v[120:121], off offset:2048 nt
.Lp1_loop:
	s_mov_b32 s16, s34
	s_mov_b32 s17, 0
	s_min_i32 s8, s34, 0x8000
	s_ashr_i32 s8, s8, 12
	s_cmp_eq_u32 s8, s56
	s_cbranch_scc1 .Lp1_keep
	s_mov_b32 s56, s8
	s_mul_hi_i32 s21, s8, 0x6000
	s_mulk_i32 s8, 0x6000
	s_add_u32 s20, s12, s8
	s_addc_u32 s21, s13, s21
	v_lshl_add_u64 v[54:55], s[20:21], 0, v[4:5]
	v_add_co_u32_e32 v30, vcc, s3, v54
	v_lshl_add_u64 v[56:57], v[54:55], 0, s[14:15]
	s_nop 0
	v_addc_co_u32_e32 v31, vcc, 0, v55, vcc
	global_load_dwordx4 v[30:33], v[30:31], off
	s_nop 0
	global_load_dwordx4 v[34:37], v[56:57], off offset:1024
	global_load_dwordx4 v[38:41], v[2:3], off offset:1024
	global_load_dwordx4 v[42:45], v[2:3], off
	global_load_dwordx4 v[46:49], v[54:55], off offset:1024
	global_load_dwordx4 v[50:53], v[54:55], off
	global_load_dwordx4 v[80:83], v[56:57], off offset:2048
	global_load_dwordx4 v[84:87], v[2:3], off offset:2048
	global_load_dwordx4 v[88:91], v[56:57], off offset:3072
	global_load_dwordx4 v[92:95], v[2:3], off offset:3072
	global_load_dwordx4 v[96:99], v[54:55], off offset:2048
	global_load_dwordx4 v[100:103], v[54:55], off offset:3072
	s_branch .Lp1_join

.Lp1_join:
	s_waitcnt vmcnt(12)
	v_mov_b32_e32 v14, v104
	v_mov_b32_e32 v15, v105
	v_mov_b32_e32 v16, v106
	v_mov_b32_e32 v17, v107
	v_mov_b32_e32 v18, v108
	v_mov_b32_e32 v19, v109
	v_mov_b32_e32 v20, v110
	v_mov_b32_e32 v21, v111
	v_mov_b32_e32 v22, v112
	v_mov_b32_e32 v23, v113
	v_mov_b32_e32 v24, v114
	v_mov_b32_e32 v25, v115
	v_mov_b32_e32 v26, v116
	v_mov_b32_e32 v27, v117
	v_mov_b32_e32 v28, v118
	v_mov_b32_e32 v29, v119
	s_mov_b32 s37, s23
	s_add_i32 s23, s23, s32
	s_cmp_ge_i32 s23, s0
	s_cselect_b32 s36, s37, s23
	s_cselect_b32 s40, 1, 0
	s_mov_b32 s34, s36
	s_cmpk_gt_i32 s34, 0x7fff
	s_cselect_b32 s20, s6, s4
	s_cselect_b32 s21, s7, s5
	s_cselect_b32 s8, 0x8000, 0
	s_sub_i32 s8, s34, s8
	s_lshl_b64 s[38:39], s[8:9], 12
	s_add_u32 s20, s20, s38
	s_addc_u32 s21, s21, s39
	v_lshl_add_u64 v[120:121], s[20:21], 0, v[4:5]
	global_load_dwordx4 v[104:107], v[120:121], off nt
	global_load_dwordx4 v[108:111], v[120:121], off offset:1024 nt
	global_load_dwordx4 v[112:115], v[120:121], off offset:3072 nt
	global_load_dwordx4 v[116:119], v[120:121], off offset:2048 nt
	s_lshl_b64 s[16:17], s[16:17], 11
	v_pk_mul_f32 v[58:59], v[16:17], v[16:17]
	v_pk_mul_f32 v[60:61], v[14:15], v[14:15]
	v_pk_mul_f32 v[62:63], v[20:21], v[20:21]
	v_pk_mul_f32 v[64:65], v[18:19], v[18:19]
	v_pk_mov_b32 v[70:71], v[60:61], v[58:59] op_sel:[1,0]
	v_mov_b32_e32 v61, v59
	v_pk_mov_b32 v[58:59], v[64:65], v[62:63] op_sel:[1,0]
	v_mov_b32_e32 v65, v63
	v_mul_f32_e32 v69, v23, v23
	v_mul_f32_e32 v66, v27, v27
	v_mul_f32_e32 v68, v29, v29
	v_pk_add_f32 v[60:61], v[70:71], v[60:61]
	v_pk_add_f32 v[58:59], v[58:59], v[64:65]
	v_mul_f32_e32 v13, v22, v22
	v_mul_f32_e32 v72, v24, v24
	v_mul_f32_e32 v73, v25, v25
	v_pk_fma_f32 v[62:63], v[26:27], v[26:27], v[66:67] op_sel_hi:[1,1,0]
	v_pk_fma_f32 v[66:67], v[28:29], v[28:29], v[68:69] op_sel_hi:[1,1,0]
	v_pk_add_f32 v[60:61], v[60:61], v[60:61] op_sel:[0,1] op_sel_hi:[1,0]
	v_pk_add_f32 v[58:59], v[58:59], v[58:59] op_sel:[0,1] op_sel_hi:[1,0]
	v_mov_b32_e32 v63, v72
	v_mov_b32_e32 v67, v73
	v_mov_b32_e32 v61, v13
	v_mov_b32_e32 v59, v69
	v_pk_add_f32 v[62:63], v[62:63], v[66:67]
	v_pk_add_f32 v[58:59], v[60:61], v[58:59]
	s_waitcnt vmcnt(15)
	v_pk_add_f32 v[76:77], v[32:33], 1.0 op_sel_hi:[1,0]
	v_pk_add_f32 v[58:59], v[58:59], v[62:63]
	v_pk_add_f32 v[74:75], v[30:31], 1.0 op_sel_hi:[1,0]
	v_add_f32_e32 v13, v58, v59
	ds_bpermute_b32 v58, v6, v13
	s_waitcnt vmcnt(14)
	v_pk_add_f32 v[122:123], v[36:37], 1.0 op_sel_hi:[1,0]
	v_pk_add_f32 v[78:79], v[34:35], 1.0 op_sel_hi:[1,0]
	s_waitcnt lgkmcnt(0)
	v_add_f32_e32 v13, v13, v58
	ds_bpermute_b32 v58, v7, v13
	s_waitcnt lgkmcnt(0)
	v_add_f32_e32 v13, v13, v58
	ds_bpermute_b32 v58, v8, v13
	s_waitcnt lgkmcnt(0)
	v_add_f32_e32 v13, v13, v58
	ds_bpermute_b32 v58, v9, v13
	s_waitcnt lgkmcnt(0)
	v_add_f32_e32 v13, v13, v58
	ds_bpermute_b32 v58, v10, v13
	s_waitcnt lgkmcnt(0)
	v_add_f32_e32 v13, v13, v58
	ds_bpermute_b32 v60, v11, v13
	v_lshl_add_u64 v[58:59], v[0:1], 0, s[16:17]
	s_waitcnt lgkmcnt(0)
	v_add_f32_e32 v13, v13, v60
	v_fmamk_f32 v13, v13, 0x3a800000, v12
	v_mul_f32_e32 v60, 0x4b800000, v13
	v_cmp_gt_f32_e32 vcc, s1, v13
	s_nop 1
	v_cndmask_b32_e32 v13, v13, v60, vcc
	v_rsq_f32_e32 v13, v13
	s_nop 0
	v_mul_f32_e32 v60, 0x45800000, v13
	v_cndmask_b32_e32 v60, v13, v60, vcc
	v_pk_mul_f32 v[16:17], v[60:61], v[16:17] op_sel_hi:[0,1]
	v_pk_mul_f32 v[14:15], v[60:61], v[14:15] op_sel_hi:[0,1]
	v_pk_mul_f32 v[20:21], v[60:61], v[20:21] op_sel_hi:[0,1]
	v_pk_mul_f32 v[18:19], v[60:61], v[18:19] op_sel_hi:[0,1]
	s_waitcnt vmcnt(12)
	v_pk_mul_f32 v[14:15], v[42:43], v[14:15]
	v_pk_mul_f32 v[16:17], v[44:45], v[16:17]
	v_pk_mul_f32 v[18:19], v[38:39], v[18:19]
	v_pk_mul_f32 v[20:21], v[40:41], v[20:21]
	s_waitcnt vmcnt(10)
	v_pk_fma_f32 v[16:17], v[76:77], v[16:17], v[52:53]
	v_pk_fma_f32 v[14:15], v[74:75], v[14:15], v[50:51]
	v_pk_fma_f32 v[20:21], v[122:123], v[20:21], v[48:49]
	v_pk_fma_f32 v[18:19], v[78:79], v[18:19], v[46:47]
	v_cvt_pk_bf16_f32 v14, v14, v15
	v_cvt_pk_bf16_f32 v15, v16, v17
	v_cvt_pk_bf16_f32 v16, v18, v19
	v_cvt_pk_bf16_f32 v17, v20, v21
	global_store_dwordx2 v[58:59], v[14:15], off sc1
	global_store_dwordx2 v[58:59], v[16:17], off offset:512 sc1
	v_pk_mul_f32 v[28:29], v[60:61], v[28:29] op_sel_hi:[0,1]
	v_pk_mul_f32 v[26:27], v[60:61], v[26:27] op_sel_hi:[0,1]
	v_pk_mul_f32 v[24:25], v[60:61], v[24:25] op_sel_hi:[0,1]
	v_pk_mul_f32 v[22:23], v[60:61], v[22:23] op_sel_hi:[0,1]
	s_waitcnt vmcnt(11)
	v_pk_add_f32 v[16:17], v[82:83], 1.0 op_sel_hi:[1,0]
	v_pk_add_f32 v[14:15], v[80:81], 1.0 op_sel_hi:[1,0]
	s_waitcnt vmcnt(10)
	v_pk_mul_f32 v[18:19], v[84:85], v[26:27]
	v_pk_mul_f32 v[20:21], v[86:87], v[28:29]
	s_waitcnt vmcnt(9)
	v_pk_add_f32 v[26:27], v[90:91], 1.0 op_sel_hi:[1,0]
	v_pk_add_f32 v[28:29], v[88:89], 1.0 op_sel_hi:[1,0]
	s_waitcnt vmcnt(8)
	v_pk_mul_f32 v[22:23], v[92:93], v[22:23]
	v_pk_mul_f32 v[24:25], v[94:95], v[24:25]
	s_waitcnt vmcnt(7)
	v_pk_fma_f32 v[16:17], v[16:17], v[20:21], v[98:99]
	v_pk_fma_f32 v[14:15], v[14:15], v[18:19], v[96:97]
	s_waitcnt vmcnt(6)
	v_pk_fma_f32 v[18:19], v[26:27], v[24:25], v[102:103]
	v_pk_fma_f32 v[20:21], v[28:29], v[22:23], v[100:101]
	v_cvt_pk_bf16_f32 v14, v14, v15
	v_cvt_pk_bf16_f32 v15, v16, v17
	v_cvt_pk_bf16_f32 v16, v20, v21
	v_cvt_pk_bf16_f32 v17, v18, v19
	global_store_dwordx2 v[58:59], v[14:15], off offset:1024 sc1
	global_store_dwordx2 v[58:59], v[16:17], off offset:1536 sc1
	s_cmp_lg_u32 s40, 0
	s_cbranch_scc0 .Lp1_loop
	s_waitcnt vmcnt(0)
